# C loop: P packed in place (no v_mov), inline-asm s_nop pads dropped, early-termination vote computed on odd tiles and checked on even tiles only
# speedup vs baseline: 1.0598x; 1.0044x over previous
; #define SBAR() __builtin_amdgcn_sched_barrier(0)
; #define PIN(x) asm volatile("" : "+v"(x))
; #define MF(a_, b_, c_) __builtin_amdgcn_mfma_f32_32x32x16_bf16(a_, b_, c_, 0, 0, 0)
; #define PVM(j_) o[(j_) % NDB] = MF(vq[(j_) & 3], pw[(j_) / NDB], o[(j_) % NDB])
; template <int KIND> DI void attn_unit(const Params& P, int b, int h, int qb, char* shm, float lam, bool dry = false) {
;     ...
;         ATT_KLD(sn, 0); ATT_XLD(sn);
;         SBAR();
;     ...
;         G1(pb0 = MF(kf[0], qr[0], negm), 0, w0, 0);  G1(pb1 = MF(kf[1], qr[0], negm), 2, w0, 1);
;         G1(pb0 = MF(kf[2], qr[1], pb0), 4, w0, 2);   G1(pb1 = MF(kf[3], qr[1], pb1), 6, w0, 3);
;         ATT_KLD(sn, 1);
;         SBAR();
;         G1(pb0 = MF(kf[0], qr[2], pb0), 8, w1, 0);   G1(pb1 = MF(kf[1], qr[2], pb1), 10, w1, 1);
;         LDV(0); SBAR();
;         G1(pb0 = MF(kf[2], qr[3], pb0), 12, w1, 2);
;         LDV(1); SBAR();
;         G1(pb1 = MF(kf[3], qr[3], pb1), 14, w1, 3);
;         LDV(2); SBAR();
;     ...
;         if (KIND == 2) { pb0 = MF(x0, ones, pb0); pb1 = MF(x1, ones, pb1); }
;         pw[0] = __builtin_bit_cast(bf16x8, w0); pw[1] = __builtin_bit_cast(bf16x8, w1);
;     ...
;         if (NDB == 4) {
;             LDV(3); PVM(0); E4(0, w0, 0); PIN(pa1); PIN(sacc); PIN(w0); SBAR();
;             LDV(4); PVM(1); E4(2, w0, 1); PIN(pa1); PIN(sacc); PIN(w0); SBAR();
;             LDV(5); PVM(2); E4(4, w0, 2); PIN(pa1); PIN(sacc); PIN(w0); SBAR();
;             LDV(6); PVM(3); E4(6, w0, 3); PIN(pa1); PIN(sacc); PIN(w0); SBAR();
;             LDV(7); PVM(4); E4(8, w1, 0); PIN(pa1); PIN(sacc); PIN(w1); SBAR();
;             LDV(8); PVM(5); E4(10, w1, 1); PIN(pa1); PIN(sacc); PIN(w1); SBAR();
;             LDV(9); PVM(6); E4(12, w1, 2); PIN(pa1); PIN(sacc); PIN(w1); SBAR();
;             LDV(10); PVM(7); E4(14, w1, 3); PIN(pa1); PIN(sacc); PIN(w1); SBAR();
;         } else {
;             LDV(3); PVM(0); E4(0, w0, 0); E4(2, w0, 1); PIN(pa1); PIN(sacc); PIN(w0); SBAR();
;             LDV(4); PVM(1); E4(4, w0, 2); E4(6, w0, 3); PIN(pa1); PIN(sacc); PIN(w0); SBAR();
;             LDV(5); PVM(2); E4(8, w1, 0); E4(10, w1, 1); PIN(pa1); PIN(sacc); PIN(w1); SBAR();
;             LDV(6); PVM(3); E4(12, w1, 2); E4(14, w1, 3); PIN(pa1); PIN(sacc); PIN(w1); SBAR();
;         }
;     ...
;         pw[2] = __builtin_bit_cast(bf16x8, w0); pw[3] = __builtin_bit_cast(bf16x8, w1);
;         lsum += sacc;
;         ATT_FIX(pb0, pb1, ATT_TILE(i + 1));
.LBB0_355:
	s_add_i32 s18, s34, 0x8400
	s_cmp_lg_u32 s34, 0x18c00
	s_cselect_b32 s29, s18, 0
	s_add_i32 s18, s29, 0
	v_add_u32_e32 v84, s18, v168
	v_add_u32_e32 v186, v84, v167
	ds_read_b128 v[100:103], v186
	ds_read_b128 v[174:177], v186 offset:512
	ds_read_b128 v[178:181], v186 offset:2048
	ds_read_b128 v[182:185], v186 offset:2560
	ds_read_b128 v[190:193], v84 offset:32768
	ds_read_b128 v[196:199], v84 offset:33280
	v_exp_f32_e32 v116, v116
	v_exp_f32_e32 v117, v117
	s_nop 0
	v_cvt_pk_bf16_f32 v152, v116, v117
	v_add_f32_e32 v84, 0, v116
	v_add_f32_e32 v84, v117, v84
	v_exp_f32_e32 v118, v118
	v_exp_f32_e32 v119, v119
	v_add_f32_e32 v84, v84, v118
	v_add_f32_e32 v84, v119, v84
	v_cvt_pk_bf16_f32 v153, v118, v119
	v_exp_f32_e32 v120, v120
	v_exp_f32_e32 v121, v121
	v_add_f32_e32 v84, v84, v120
	v_add_f32_e32 v187, v121, v84
	v_cvt_pk_bf16_f32 v154, v120, v121
	s_waitcnt lgkmcnt(5)
	v_mfma_f32_32x32x16_bf16 v[84:99], v[100:103], v[144:147], v[20:35]
	v_exp_f32_e32 v122, v122
	v_exp_f32_e32 v123, v123
	s_waitcnt lgkmcnt(4)
	v_mfma_f32_32x32x16_bf16 v[100:115], v[174:177], v[144:147], v[20:35]
	s_add_i32 s18, s34, 0
	v_exp_f32_e32 v124, v124
	v_exp_f32_e32 v125, v125
	s_waitcnt lgkmcnt(3)
	v_mfma_f32_32x32x16_bf16 v[84:99], v[178:181], v[140:143], v[84:99]
	v_add3_u32 v68, s18, v170, v171
	v_add_f32_e32 v72, v187, v122
	v_cvt_pk_bf16_f32 v148, v124, v125
	v_add_u32_e32 v164, v68, v172
	s_waitcnt lgkmcnt(0)
	v_add_f32_e32 v187, v123, v72
	v_cvt_pk_bf16_f32 v155, v122, v123
	v_mfma_f32_32x32x16_bf16 v[100:115], v[182:185], v[140:143], v[100:115]
	ds_read_b128 v[72:75], v186 offset:4096
	ds_read_b128 v[80:83], v186 offset:4608
	ds_read_b128 v[174:177], v186 offset:6144
	ds_read_b128 v[178:181], v186 offset:6656
	s_waitcnt lgkmcnt(3)
	v_mfma_f32_32x32x16_bf16 v[84:99], v[72:75], v[136:139], v[84:99]
	v_add_f32_e32 v72, v187, v124
	v_add_f32_e32 v72, v125, v72
	s_waitcnt lgkmcnt(2)
	v_mfma_f32_32x32x16_bf16 v[100:115], v[80:83], v[136:139], v[100:115]
	v_exp_f32_e32 v126, v126
	v_exp_f32_e32 v127, v127
	v_add_f32_e32 v72, v72, v126
	v_add_f32_e32 v80, v127, v72
	v_cvt_pk_bf16_f32 v149, v126, v127
	ds_read_b64_tr_b16 v[72:73], v164 offset:16384
	ds_read_b64_tr_b16 v[74:75], v164 offset:16896
	s_waitcnt lgkmcnt(3)
	v_mfma_f32_32x32x16_bf16 v[84:99], v[174:177], v[132:135], v[84:99]
	v_exp_f32_e32 v128, v128
	v_exp_f32_e32 v129, v129
	v_add_f32_e32 v80, v80, v128
	v_add_f32_e32 v174, v129, v80
	v_cvt_pk_bf16_f32 v150, v128, v129
	ds_read_b64_tr_b16 v[80:81], v164 offset:20480
	ds_read_b64_tr_b16 v[82:83], v164 offset:20992
	s_waitcnt lgkmcnt(4)
	v_mfma_f32_32x32x16_bf16 v[100:115], v[178:181], v[132:135], v[100:115]
	v_exp_f32_e32 v130, v130
	v_exp_f32_e32 v131, v131
	v_add_f32_e32 v151, v174, v130
	v_add_f32_e32 v174, v131, v151
	v_cvt_pk_bf16_f32 v151, v130, v131
	ds_read_b64_tr_b16 v[124:125], v164 offset:17408
	ds_read_b64_tr_b16 v[126:127], v164 offset:17920
	v_mfma_f32_32x32x16_bf16 v[84:99], v[190:193], v[0:3], v[84:99]
	v_exp_f32_e32 v4, v4
	v_exp_f32_e32 v5, v5
	v_exp_f32_e32 v6, v6
	v_exp_f32_e32 v7, v7
	v_cvt_pk_bf16_f32 v190, v4, v5
	v_mfma_f32_32x32x16_bf16 v[100:115], v[196:199], v[0:3], v[100:115]
	ds_read_b64_tr_b16 v[68:69], v164 offset:21504
	ds_read_b64_tr_b16 v[70:71], v164 offset:22016
	s_waitcnt lgkmcnt(6)
	v_mfma_f32_32x32x16_bf16 v[52:67], v[72:75], v[152:155], v[52:67]
	v_add_f32_e32 v72, v4, v174
	v_add_f32_e32 v76, v5, v72
	v_add_f32_e32 v73, v6, v76
	v_add_f32_e32 v76, v7, v73
	v_cvt_pk_bf16_f32 v191, v6, v7
	v_exp_f32_e32 v8, v8
	v_exp_f32_e32 v9, v9
	s_waitcnt lgkmcnt(4)
	v_mfma_f32_32x32x16_bf16 v[36:51], v[80:83], v[152:155], v[36:51]
	v_exp_f32_e32 v10, v10
	v_exp_f32_e32 v11, v11
	v_add_f32_e32 v74, v76, v8
	ds_read_b64_tr_b16 v[116:117], v164 offset:18432
	ds_read_b64_tr_b16 v[118:119], v164 offset:18944
	v_add_f32_e32 v75, v9, v74
	v_add_f32_e32 v75, v10, v75
	v_cvt_pk_bf16_f32 v192, v8, v9
	v_add_f32_e32 v76, v11, v75
	v_cvt_pk_bf16_f32 v193, v10, v11
	v_exp_f32_e32 v12, v12
	s_waitcnt lgkmcnt(4)
	v_mfma_f32_32x32x16_bf16 v[52:67], v[124:127], v[148:151], v[52:67]
	v_exp_f32_e32 v13, v13
	v_exp_f32_e32 v14, v14
	ds_read_b64_tr_b16 v[120:121], v164 offset:22528
	ds_read_b64_tr_b16 v[122:123], v164 offset:23040
	v_exp_f32_e32 v15, v15
	v_add_f32_e32 v72, v76, v12
	v_add_f32_e32 v76, v13, v72
	v_cvt_pk_bf16_f32 v152, v12, v13
	v_add_f32_e32 v73, v14, v76
	v_add_f32_e32 v76, v15, v73
	v_cvt_pk_bf16_f32 v153, v14, v15
	s_waitcnt lgkmcnt(4)
	v_mfma_f32_32x32x16_bf16 v[36:51], v[68:71], v[148:151], v[36:51]
	v_exp_f32_e32 v16, v16
	v_exp_f32_e32 v17, v17
	v_exp_f32_e32 v18, v18
	v_exp_f32_e32 v19, v19
	ds_read_b64_tr_b16 v[124:125], v164 offset:19456
	ds_read_b64_tr_b16 v[126:127], v164 offset:19968
	v_add_f32_e32 v68, v76, v16
	v_add_f32_e32 v68, v17, v68
	v_cvt_pk_bf16_f32 v154, v16, v17
	v_cvt_pk_bf16_f32 v155, v18, v19
	v_add_f32_e32 v68, v18, v68
	v_add_f32_e32 v68, v19, v68
	s_cmp_lg_u32 s22, s35
	s_cbranch_scc1 .LBB0_357
	v_cndmask_b32_e64 v4, v84, v245, s[48:49]
	v_cndmask_b32_e64 v100, v100, v245, s[50:51]
	v_cndmask_b32_e64 v85, v245, v85, s[52:53]
	v_cndmask_b32_e64 v84, v4, v84, s[52:53]
	v_cndmask_b32_e64 v101, v101, v245, s[54:55]
	v_cndmask_b32_e64 v86, v86, v245, s[56:57]
	v_cndmask_b32_e64 v102, v102, v245, s[58:59]
	v_cndmask_b32_e64 v87, v87, v245, s[60:61]
	v_cndmask_b32_e64 v103, v103, v245, s[62:63]
	v_cndmask_b32_e64 v88, v88, v245, s[64:65]
	v_cndmask_b32_e64 v104, v104, v245, s[66:67]
	v_cndmask_b32_e64 v89, v89, v245, s[68:69]
	v_cndmask_b32_e64 v105, v105, v245, s[70:71]
	v_cndmask_b32_e64 v90, v90, v245, s[72:73]
	v_cndmask_b32_e64 v106, v106, v245, s[74:75]
	v_cndmask_b32_e64 v91, v91, v245, s[76:77]
	v_cndmask_b32_e64 v107, v107, v245, s[78:79]
	v_cndmask_b32_e64 v92, v92, v245, s[80:81]
	v_cndmask_b32_e64 v108, v108, v245, s[82:83]
	v_cndmask_b32_e64 v93, v93, v245, s[84:85]
	v_cndmask_b32_e64 v109, v109, v245, s[86:87]
	v_cndmask_b32_e64 v94, v94, v245, s[88:89]
	v_cndmask_b32_e64 v110, v110, v245, s[90:91]
	v_cndmask_b32_e64 v95, v95, v245, s[92:93]
	v_cndmask_b32_e64 v111, v111, v245, s[94:95]
	v_cndmask_b32_e64 v96, v96, v245, s[96:97]
	v_cndmask_b32_e64 v112, v112, v245, s[4:5]
	v_cndmask_b32_e64 v97, v97, v245, s[6:7]
	v_cndmask_b32_e64 v113, v113, v245, s[8:9]
	v_cndmask_b32_e64 v98, v98, v245, s[10:11]
	v_cndmask_b32_e64 v114, v114, v245, s[12:13]
	v_cndmask_b32_e64 v99, v99, v245, s[14:15]
	v_cndmask_b32_e64 v115, v115, v245, s[16:17]
; template <int KIND> DI void attn_unit(const Params& P, int b, int h, int qb, char* shm, float lam, bool dry = false) {
;     ...
;         ATT_FIX(pb0, pb1, ATT_TILE(i + 1));
;         float rm, rm2;
;         if (NDB == 4) {
;             LDV(11); PVM(8); rm = max3f(pb0[0], pb0[1], pb1[0]); rm2 = max3f(pb0[2], pb0[3], pb1[1]); PIN(rm); PIN(rm2); SBAR();
;             LDV(12); PVM(9); rm = max3f(rm, pb1[2], pb1[3]); rm2 = max3f(rm2, pb0[4], pb0[5]); PIN(rm); PIN(rm2); SBAR();
;             LDV(13); PVM(10); rm = max3f(rm, pb0[6], pb0[7]); rm2 = max3f(rm2, pb1[4], pb1[5]); PIN(rm); PIN(rm2); SBAR();
;             LDV(14); PVM(11); rm = max3f(rm, pb1[6], pb1[7]); rm2 = max3f(rm2, pb0[8], pb0[9]); PIN(rm); PIN(rm2); SBAR();
;             LDV(15); PVM(12); rm = max3f(rm, pb0[10], pb0[11]); rm2 = max3f(rm2, pb1[8], pb1[9]); PIN(rm); PIN(rm2); SBAR();
;             PVM(13); rm = max3f(rm, pb1[10], pb1[11]); rm2 = max3f(rm2, pb0[12], pb0[13]); PIN(rm); PIN(rm2); SBAR();
;             PVM(14); rm = max3f(rm, pb0[14], pb0[15]); rm2 = max3f(rm2, pb1[12], pb1[13]); PIN(rm); PIN(rm2); SBAR();
;             PVM(15); rm = max3f(rm, pb1[14], pb1[15]); PIN(rm); SBAR();
;         } else {
;             LDV(7); PVM(4); rm = max3f(pb0[0], pb0[1], pb1[0]); rm2 = max3f(pb0[2], pb0[3], pb1[1]); rm = max3f(rm, pb1[2], pb1[3]); rm2 = max3f(rm2, pb0[4], pb0[5]); PIN(rm); PIN(rm2); SBAR();
;             PVM(5); rm = max3f(rm, pb0[6], pb0[7]); rm2 = max3f(rm2, pb1[4], pb1[5]); rm = max3f(rm, pb1[6], pb1[7]); rm2 = max3f(rm2, pb0[8], pb0[9]); PIN(rm); PIN(rm2); SBAR();
;             PVM(6); rm = max3f(rm, pb0[10], pb0[11]); rm2 = max3f(rm2, pb1[8], pb1[9]); rm = max3f(rm, pb1[10], pb1[11]); rm2 = max3f(rm2, pb0[12], pb0[13]); PIN(rm); PIN(rm2); SBAR();
;             PVM(7); rm = max3f(rm, pb0[14], pb0[15]); rm2 = max3f(rm2, pb1[12], pb1[13]); rm = max3f(rm, pb1[14], pb1[15]); PIN(rm); PIN(rm2); SBAR();
;         }
;     ...
;         rm = swapmax(max3f(rm, rm2, rm2));
;         if (KIND == 2) {
;             const u32x2 kx = *(const LAS u32x2*)(shm3 + sc + 32768);
;             const float xk0 = __uint_as_float(kx.x << 16) + __uint_as_float(kx.x & 0xffff0000u) + __uint_as_float(kx.y << 16);
;             const float ltot = swapsum(lsum);
;             const bool ok = (qkmax + cb + xk0) < (mhat + __builtin_amdgcn_logf(ltot) - 54.0f);
;             const bool allok = __all(ok) && !(ATT_TILE(i) > wt_hi);
.LBB0_357:
	s_add_i32 s19, s20, 2
	s_cmp_lt_i32 s19, 0
	s_cselect_b64 s[38:39], -1, 0
	s_cmp_gt_i32 s19, s36
	s_waitcnt lgkmcnt(4)
	v_mfma_f32_32x32x16_bf16 v[52:67], v[116:119], v[190:193], v[52:67]
	s_cselect_b64 vcc, -1, 0
	s_or_b64 vcc, s[38:39], vcc
	s_cbranch_vccz .Lct1_nomask
	v_mov_b32_e32 v84, v245
	v_mov_b32_e32 v85, v245
	v_mov_b32_e32 v86, v245
	v_mov_b32_e32 v87, v245
	v_mov_b32_e32 v88, v245
	v_mov_b32_e32 v89, v245
	v_mov_b32_e32 v90, v245
	v_mov_b32_e32 v91, v245
	v_mov_b32_e32 v92, v245
	v_mov_b32_e32 v93, v245
	v_mov_b32_e32 v94, v245
	v_mov_b32_e32 v95, v245
	v_mov_b32_e32 v96, v245
	v_mov_b32_e32 v97, v245
	v_mov_b32_e32 v98, v245
	v_mov_b32_e32 v99, v245
	v_mov_b32_e32 v100, v245
	v_mov_b32_e32 v101, v245
	v_mov_b32_e32 v102, v245
	v_mov_b32_e32 v103, v245
	v_mov_b32_e32 v104, v245
	v_mov_b32_e32 v105, v245
	v_mov_b32_e32 v106, v245
	v_mov_b32_e32 v107, v245
	v_mov_b32_e32 v108, v245
	v_mov_b32_e32 v109, v245
	v_mov_b32_e32 v110, v245
	v_mov_b32_e32 v111, v245
	v_mov_b32_e32 v112, v245
	v_mov_b32_e32 v113, v245
	v_mov_b32_e32 v114, v245
	v_mov_b32_e32 v115, v245
.Lct1_nomask:
	v_add_f32_e32 v169, v169, v68
	ds_read_b64_tr_b16 v[128:129], v164 offset:23552
	ds_read_b64_tr_b16 v[130:131], v164 offset:24064
	v_max3_f32 v116, v84, v85, v100
	v_max3_f32 v117, v86, v87, v101
	v_max3_f32 v116, v116, v102, v103
	v_max3_f32 v117, v117, v88, v89
	s_waitcnt lgkmcnt(4)
	v_mfma_f32_32x32x16_bf16 v[36:51], v[120:123], v[190:193], v[36:51]
	v_max3_f32 v116, v116, v90, v91
	v_max3_f32 v117, v117, v104, v105
	v_max3_f32 v116, v116, v106, v107
	v_max3_f32 v117, v117, v92, v93
	s_waitcnt lgkmcnt(2)
	v_mfma_f32_32x32x16_bf16 v[52:67], v[124:127], v[152:155], v[52:67]
	v_max3_f32 v116, v116, v94, v95
	v_max3_f32 v117, v117, v108, v109
	v_max3_f32 v116, v116, v110, v111
	v_max3_f32 v117, v117, v96, v97
	s_waitcnt lgkmcnt(0)
	v_mfma_f32_32x32x16_bf16 v[36:51], v[128:131], v[152:155], v[36:51]
	v_max3_f32 v116, v116, v98, v99
	v_max3_f32 v117, v117, v112, v113
	v_max3_f32 v116, v116, v114, v115
	v_max3_f32 v116, v116, v117, v117
	v_mov_b32_e32 v117, v116
	s_nop 1
	v_permlane32_swap_b32_e32 v116, v117
.LBB0_359:
	v_cmp_ge_i32_e64 s[18:19], s31, v173
	s_and_b64 vcc, exec, s[18:19]
	s_cbranch_vccnz .LBB0_362
	v_max_f32_e32 v116, v116, v116
	v_max_f32_e32 v117, v117, v117
	v_max_f32_e32 v116, v116, v117
	v_cmp_lt_f32_e32 vcc, s3, v116
	s_cbranch_vccz .LBB0_362
	v_max_f32_e32 v116, v116, v116
	v_max_f32_e32 v117, 0, v116
	v_exp_f32_e64 v116, -v117
	v_add_f32_e32 v165, v165, v117
	v_sub_f32_e32 v99, v99, v117
	v_sub_f32_e32 v98, v98, v117
	v_pk_mul_f32 v[50:51], v[50:51], v[116:117] op_sel_hi:[1,0]
	v_pk_mul_f32 v[48:49], v[48:49], v[116:117] op_sel_hi:[1,0]
	v_pk_mul_f32 v[46:47], v[46:47], v[116:117] op_sel_hi:[1,0]
	v_pk_mul_f32 v[44:45], v[44:45], v[116:117] op_sel_hi:[1,0]
	v_pk_mul_f32 v[42:43], v[42:43], v[116:117] op_sel_hi:[1,0]
	v_pk_mul_f32 v[40:41], v[40:41], v[116:117] op_sel_hi:[1,0]
	v_pk_mul_f32 v[38:39], v[38:39], v[116:117] op_sel_hi:[1,0]
	v_pk_mul_f32 v[36:37], v[36:37], v[116:117] op_sel_hi:[1,0]
	v_pk_mul_f32 v[66:67], v[66:67], v[116:117] op_sel_hi:[1,0]
	v_pk_mul_f32 v[64:65], v[64:65], v[116:117] op_sel_hi:[1,0]
	v_pk_mul_f32 v[62:63], v[62:63], v[116:117] op_sel_hi:[1,0]
	v_pk_mul_f32 v[60:61], v[60:61], v[116:117] op_sel_hi:[1,0]
	v_pk_mul_f32 v[58:59], v[58:59], v[116:117] op_sel_hi:[1,0]
	v_pk_mul_f32 v[56:57], v[56:57], v[116:117] op_sel_hi:[1,0]
	v_pk_mul_f32 v[54:55], v[54:55], v[116:117] op_sel_hi:[1,0]
	v_pk_mul_f32 v[52:53], v[52:53], v[116:117] op_sel_hi:[1,0]
	v_sub_f32_e32 v97, v97, v117
	v_sub_f32_e32 v96, v96, v117
	v_sub_f32_e32 v95, v95, v117
	v_sub_f32_e32 v94, v94, v117
	v_sub_f32_e32 v93, v93, v117
	v_sub_f32_e32 v92, v92, v117
	v_sub_f32_e32 v91, v91, v117
	v_sub_f32_e32 v90, v90, v117
	v_sub_f32_e32 v89, v89, v117
	v_sub_f32_e32 v88, v88, v117
	v_sub_f32_e32 v87, v87, v117
	v_sub_f32_e32 v86, v86, v117
	v_sub_f32_e32 v85, v85, v117
	v_sub_f32_e32 v84, v84, v117
	v_sub_f32_e32 v115, v115, v117
	v_sub_f32_e32 v114, v114, v117
	v_sub_f32_e32 v113, v113, v117
	v_sub_f32_e32 v112, v112, v117
	v_sub_f32_e32 v111, v111, v117
	v_sub_f32_e32 v110, v110, v117
	v_sub_f32_e32 v109, v109, v117
	v_sub_f32_e32 v108, v108, v117
	v_sub_f32_e32 v107, v107, v117
	v_sub_f32_e32 v106, v106, v117
	v_sub_f32_e32 v105, v105, v117
	v_sub_f32_e32 v104, v104, v117
	v_sub_f32_e32 v103, v103, v117
	v_sub_f32_e32 v102, v102, v117
	v_sub_f32_e32 v101, v101, v117
	v_sub_f32_e32 v100, v100, v117
	v_sub_f32_e32 v35, v35, v117
	v_sub_f32_e32 v34, v34, v117
	v_sub_f32_e32 v33, v33, v117
	v_sub_f32_e32 v32, v32, v117
	v_sub_f32_e32 v31, v31, v117
	v_sub_f32_e32 v30, v30, v117
	v_sub_f32_e32 v29, v29, v117
	v_sub_f32_e32 v28, v28, v117
	v_sub_f32_e32 v27, v27, v117
	v_sub_f32_e32 v26, v26, v117
	v_sub_f32_e32 v25, v25, v117
	v_sub_f32_e32 v24, v24, v117
	v_sub_f32_e32 v23, v23, v117
	v_sub_f32_e32 v22, v22, v117
	v_sub_f32_e32 v21, v21, v117
	v_sub_f32_e32 v20, v20, v117
	v_mul_f32_e32 v169, v169, v116

; template <int KIND> DI void attn_unit(const Params& P, int b, int h, int qb, char* shm, float lam, bool dry = false) {
;     ...
;     f32x16 pa0, pa1, pb0, pb1;
;     bf16x8 kf[4], x0, x1;
;     ATT_KLD(0, 0); ATT_XLD(0);
;     pa0 = MF(kf[0], qr[0], negm); pa1 = MF(kf[1], qr[0], negm); pa0 = MF(kf[2], qr[1], pa0); pa1 = MF(kf[3], qr[1], pa1);
;     SBAR(); ATT_KLD(0, 1); SBAR();
;     pa0 = MF(kf[0], qr[2], pa0); pa1 = MF(kf[1], qr[2], pa1); pa0 = MF(kf[2], qr[3], pa0); pa1 = MF(kf[3], qr[3], pa1);
;     if (KIND == 2) { pa0 = MF(x0, ones, pa0); pa1 = MF(x1, ones, pa1); }
;     ATT_FIX(pa0, pa1, ATT_TILE(0));
;     { float rm = max3f(pa0[0], pa0[1], pa1[0]), rm2 = max3f(pa0[2], pa0[3], pa1[1]); rm = max3f(rm, pa1[2], pa1[3]);
; #pragma unroll
;       for (int r = 4; r < 16; r += 4) { rm = max3f(rm, pa0[r], pa0[r + 1]); rm2 = max3f(rm2, pa0[r + 2], pa0[r + 3]); rm = max3f(rm, pa1[r], pa1[r + 1]); rm2 = max3f(rm2, pa1[r + 2], pa1[r + 3]); }
;       rm = swapmax(max3f(rm, rm2, rm2)); ATT_DECIDE(pa0, pa1, rm); }
;     for (int i = 0; i < nt_eff; ++i) {
;         ATT_STEP_BAR(i);
;         const int sn = (sc == 3 * SLOT) ? 0 : sc + SLOT;
;         const lds_cptr vp = shm3 + sc + 16384 + vlane;
;         bf16x8 vq[4]; bf16x8 pw[4]; u32x4 w0, w1; float sacc = 0.f;
;     ...
;         ATT_KLD(sn, 0); ATT_XLD(sn);
;         SBAR();
;     ...
;         G1(pb0 = MF(kf[0], qr[0], negm), 0, w0, 0);  G1(pb1 = MF(kf[1], qr[0], negm), 2, w0, 1);
;         G1(pb0 = MF(kf[2], qr[1], pb0), 4, w0, 2);   G1(pb1 = MF(kf[3], qr[1], pb1), 6, w0, 3);
;         ATT_KLD(sn, 1);
;         SBAR();
;         G1(pb0 = MF(kf[0], qr[2], pb0), 8, w1, 0);   G1(pb1 = MF(kf[1], qr[2], pb1), 10, w1, 1);
;         LDV(0); SBAR();
;         G1(pb0 = MF(kf[2], qr[3], pb0), 12, w1, 2);
;         LDV(1); SBAR();
;         G1(pb1 = MF(kf[3], qr[3], pb1), 14, w1, 3);
;         LDV(2); SBAR();
;     ...
;         if (KIND == 2) { pb0 = MF(x0, ones, pb0); pb1 = MF(x1, ones, pb1); }
;         pw[0] = __builtin_bit_cast(bf16x8, w0); pw[1] = __builtin_bit_cast(bf16x8, w1);
;     ...
;         if (NDB == 4) {
;             LDV(3); PVM(0); E4(0, w0, 0); PIN(pa1); PIN(sacc); PIN(w0); SBAR();
;             LDV(4); PVM(1); E4(2, w0, 1); PIN(pa1); PIN(sacc); PIN(w0); SBAR();
;             LDV(5); PVM(2); E4(4, w0, 2); PIN(pa1); PIN(sacc); PIN(w0); SBAR();
;             LDV(6); PVM(3); E4(6, w0, 3); PIN(pa1); PIN(sacc); PIN(w0); SBAR();
.Lct2_353:
	s_andn2_b64 vcc, exec, s[18:19]
	s_cbranch_vccnz .Lct2_355
	s_add_i32 s31, s35, 1
.Lct2_355:
	s_add_i32 s18, s34, 0x8400
	s_cmp_lg_u32 s34, 0x18c00
	s_cselect_b32 s29, s18, 0
	s_add_i32 s18, s29, 0
	v_add_u32_e32 v116, s18, v168
	v_add_u32_e32 v186, v116, v167
	ds_read_b128 v[4:7], v186
	ds_read_b128 v[174:177], v186 offset:512
	ds_read_b128 v[178:181], v186 offset:2048
	ds_read_b128 v[182:185], v186 offset:2560
	ds_read_b128 v[190:193], v116 offset:32768
	ds_read_b128 v[196:199], v116 offset:33280
	v_exp_f32_e32 v84, v84
	v_exp_f32_e32 v85, v85
	s_nop 0
	v_cvt_pk_bf16_f32 v152, v84, v85
	v_add_f32_e32 v116, 0, v84
	v_add_f32_e32 v116, v85, v116
	v_exp_f32_e32 v86, v86
	v_exp_f32_e32 v87, v87
	v_add_f32_e32 v116, v116, v86
	v_add_f32_e32 v116, v87, v116
	v_cvt_pk_bf16_f32 v153, v86, v87
	v_exp_f32_e32 v88, v88
	v_exp_f32_e32 v89, v89
	v_add_f32_e32 v116, v116, v88
	v_add_f32_e32 v187, v89, v116
	v_cvt_pk_bf16_f32 v154, v88, v89
	s_waitcnt lgkmcnt(5)
	v_mfma_f32_32x32x16_bf16 v[116:131], v[4:7], v[144:147], v[20:35]
	v_exp_f32_e32 v90, v90
	v_exp_f32_e32 v91, v91
	s_waitcnt lgkmcnt(4)
	v_mfma_f32_32x32x16_bf16 v[4:19], v[174:177], v[144:147], v[20:35]
	s_add_i32 s18, s34, 0
	v_exp_f32_e32 v92, v92
	v_exp_f32_e32 v93, v93
	s_waitcnt lgkmcnt(3)
	v_mfma_f32_32x32x16_bf16 v[116:131], v[178:181], v[140:143], v[116:131]
	v_add3_u32 v68, s18, v170, v171
	v_add_f32_e32 v72, v187, v90
	v_cvt_pk_bf16_f32 v148, v92, v93
	v_add_u32_e32 v164, v68, v172
	s_waitcnt lgkmcnt(0)
	v_add_f32_e32 v187, v91, v72
	v_cvt_pk_bf16_f32 v155, v90, v91
	v_mfma_f32_32x32x16_bf16 v[4:19], v[182:185], v[140:143], v[4:19]
	ds_read_b128 v[72:75], v186 offset:4096
	ds_read_b128 v[80:83], v186 offset:4608
	ds_read_b128 v[174:177], v186 offset:6144
	ds_read_b128 v[178:181], v186 offset:6656
	s_waitcnt lgkmcnt(3)
	v_mfma_f32_32x32x16_bf16 v[116:131], v[72:75], v[136:139], v[116:131]
	v_add_f32_e32 v72, v187, v92
	v_add_f32_e32 v72, v93, v72
	s_waitcnt lgkmcnt(2)
	v_mfma_f32_32x32x16_bf16 v[4:19], v[80:83], v[136:139], v[4:19]
	v_exp_f32_e32 v94, v94
	v_exp_f32_e32 v95, v95
	v_add_f32_e32 v72, v72, v94
	v_add_f32_e32 v80, v95, v72
	v_cvt_pk_bf16_f32 v149, v94, v95
	ds_read_b64_tr_b16 v[72:73], v164 offset:16384
	ds_read_b64_tr_b16 v[74:75], v164 offset:16896
	s_waitcnt lgkmcnt(3)
	v_mfma_f32_32x32x16_bf16 v[116:131], v[174:177], v[132:135], v[116:131]
	v_exp_f32_e32 v96, v96
	v_exp_f32_e32 v97, v97
	v_add_f32_e32 v80, v80, v96
	v_add_f32_e32 v174, v97, v80
	v_cvt_pk_bf16_f32 v150, v96, v97
	ds_read_b64_tr_b16 v[80:81], v164 offset:20480
	ds_read_b64_tr_b16 v[82:83], v164 offset:20992
	s_waitcnt lgkmcnt(4)
	v_mfma_f32_32x32x16_bf16 v[4:19], v[178:181], v[132:135], v[4:19]
	v_exp_f32_e32 v98, v98
	v_exp_f32_e32 v99, v99
	v_add_f32_e32 v151, v174, v98
	v_add_f32_e32 v174, v99, v151
	v_cvt_pk_bf16_f32 v151, v98, v99
	ds_read_b64_tr_b16 v[92:93], v164 offset:17408
	ds_read_b64_tr_b16 v[94:95], v164 offset:17920
	v_mfma_f32_32x32x16_bf16 v[116:131], v[190:193], v[0:3], v[116:131]
	v_exp_f32_e32 v100, v100
	v_exp_f32_e32 v101, v101
	v_exp_f32_e32 v102, v102
	v_exp_f32_e32 v103, v103
	v_cvt_pk_bf16_f32 v190, v100, v101
	v_mfma_f32_32x32x16_bf16 v[4:19], v[196:199], v[0:3], v[4:19]
	ds_read_b64_tr_b16 v[68:69], v164 offset:21504
	ds_read_b64_tr_b16 v[70:71], v164 offset:22016
	s_waitcnt lgkmcnt(6)
	v_mfma_f32_32x32x16_bf16 v[52:67], v[72:75], v[152:155], v[52:67]
	v_add_f32_e32 v72, v100, v174
	v_add_f32_e32 v76, v101, v72
	v_add_f32_e32 v73, v102, v76
	v_add_f32_e32 v76, v103, v73
	v_cvt_pk_bf16_f32 v191, v102, v103
	v_exp_f32_e32 v104, v104
	v_exp_f32_e32 v105, v105
	s_waitcnt lgkmcnt(4)
	v_mfma_f32_32x32x16_bf16 v[36:51], v[80:83], v[152:155], v[36:51]
	v_exp_f32_e32 v106, v106
	v_exp_f32_e32 v107, v107
	v_add_f32_e32 v74, v76, v104
	ds_read_b64_tr_b16 v[84:85], v164 offset:18432
	ds_read_b64_tr_b16 v[86:87], v164 offset:18944
	v_add_f32_e32 v75, v105, v74
	v_add_f32_e32 v75, v106, v75
	v_cvt_pk_bf16_f32 v192, v104, v105
	v_add_f32_e32 v76, v107, v75
	v_cvt_pk_bf16_f32 v193, v106, v107
	v_exp_f32_e32 v108, v108
	s_waitcnt lgkmcnt(4)
	v_mfma_f32_32x32x16_bf16 v[52:67], v[92:95], v[148:151], v[52:67]
	v_exp_f32_e32 v109, v109
	v_exp_f32_e32 v110, v110
	ds_read_b64_tr_b16 v[88:89], v164 offset:22528
	ds_read_b64_tr_b16 v[90:91], v164 offset:23040
	v_exp_f32_e32 v111, v111
	v_add_f32_e32 v72, v76, v108
	v_add_f32_e32 v76, v109, v72
	v_cvt_pk_bf16_f32 v152, v108, v109
	v_add_f32_e32 v73, v110, v76
	v_add_f32_e32 v76, v111, v73
	v_cvt_pk_bf16_f32 v153, v110, v111
	s_waitcnt lgkmcnt(4)
	v_mfma_f32_32x32x16_bf16 v[36:51], v[68:71], v[148:151], v[36:51]
	v_exp_f32_e32 v112, v112
	v_exp_f32_e32 v113, v113
	v_exp_f32_e32 v114, v114
	v_exp_f32_e32 v115, v115
	ds_read_b64_tr_b16 v[92:93], v164 offset:19456
	ds_read_b64_tr_b16 v[94:95], v164 offset:19968
	v_add_f32_e32 v68, v76, v112
	v_add_f32_e32 v68, v113, v68
	v_cvt_pk_bf16_f32 v154, v112, v113
	v_cvt_pk_bf16_f32 v155, v114, v115
	v_add_f32_e32 v68, v114, v68
	v_add_f32_e32 v68, v115, v68
	s_cmp_lg_u32 s22, s35
	s_cbranch_scc1 .Lct2_357
	v_cndmask_b32_e64 v100, v116, v245, s[48:49]
	v_cndmask_b32_e64 v4, v4, v245, s[50:51]
	v_cndmask_b32_e64 v117, v245, v117, s[52:53]
	v_cndmask_b32_e64 v116, v100, v116, s[52:53]
	v_cndmask_b32_e64 v5, v5, v245, s[54:55]
	v_cndmask_b32_e64 v118, v118, v245, s[56:57]
	v_cndmask_b32_e64 v6, v6, v245, s[58:59]
	v_cndmask_b32_e64 v119, v119, v245, s[60:61]
	v_cndmask_b32_e64 v7, v7, v245, s[62:63]
	v_cndmask_b32_e64 v120, v120, v245, s[64:65]
	v_cndmask_b32_e64 v8, v8, v245, s[66:67]
	v_cndmask_b32_e64 v121, v121, v245, s[68:69]
	v_cndmask_b32_e64 v9, v9, v245, s[70:71]
	v_cndmask_b32_e64 v122, v122, v245, s[72:73]
	v_cndmask_b32_e64 v10, v10, v245, s[74:75]
	v_cndmask_b32_e64 v123, v123, v245, s[76:77]
	v_cndmask_b32_e64 v11, v11, v245, s[78:79]
	v_cndmask_b32_e64 v124, v124, v245, s[80:81]
	v_cndmask_b32_e64 v12, v12, v245, s[82:83]
	v_cndmask_b32_e64 v125, v125, v245, s[84:85]
	v_cndmask_b32_e64 v13, v13, v245, s[86:87]
	v_cndmask_b32_e64 v126, v126, v245, s[88:89]
	v_cndmask_b32_e64 v14, v14, v245, s[90:91]
	v_cndmask_b32_e64 v127, v127, v245, s[92:93]
	v_cndmask_b32_e64 v15, v15, v245, s[94:95]
	v_cndmask_b32_e64 v128, v128, v245, s[96:97]
	v_cndmask_b32_e64 v16, v16, v245, s[4:5]
	v_cndmask_b32_e64 v129, v129, v245, s[6:7]
	v_cndmask_b32_e64 v17, v17, v245, s[8:9]
	v_cndmask_b32_e64 v130, v130, v245, s[10:11]
	v_cndmask_b32_e64 v18, v18, v245, s[12:13]
	v_cndmask_b32_e64 v131, v131, v245, s[14:15]
	v_cndmask_b32_e64 v19, v19, v245, s[16:17]
; template <int KIND> DI void attn_unit(const Params& P, int b, int h, int qb, char* shm, float lam, bool dry = false) {
;     ...
;         ATT_FIX(pb0, pb1, ATT_TILE(i + 1));
;         float rm, rm2;
;         if (NDB == 4) {
;             LDV(11); PVM(8); rm = max3f(pb0[0], pb0[1], pb1[0]); rm2 = max3f(pb0[2], pb0[3], pb1[1]); PIN(rm); PIN(rm2); SBAR();
;             LDV(12); PVM(9); rm = max3f(rm, pb1[2], pb1[3]); rm2 = max3f(rm2, pb0[4], pb0[5]); PIN(rm); PIN(rm2); SBAR();
;             LDV(13); PVM(10); rm = max3f(rm, pb0[6], pb0[7]); rm2 = max3f(rm2, pb1[4], pb1[5]); PIN(rm); PIN(rm2); SBAR();
;             LDV(14); PVM(11); rm = max3f(rm, pb1[6], pb1[7]); rm2 = max3f(rm2, pb0[8], pb0[9]); PIN(rm); PIN(rm2); SBAR();
;             LDV(15); PVM(12); rm = max3f(rm, pb0[10], pb0[11]); rm2 = max3f(rm2, pb1[8], pb1[9]); PIN(rm); PIN(rm2); SBAR();
;             PVM(13); rm = max3f(rm, pb1[10], pb1[11]); rm2 = max3f(rm2, pb0[12], pb0[13]); PIN(rm); PIN(rm2); SBAR();
;             PVM(14); rm = max3f(rm, pb0[14], pb0[15]); rm2 = max3f(rm2, pb1[12], pb1[13]); PIN(rm); PIN(rm2); SBAR();
;             PVM(15); rm = max3f(rm, pb1[14], pb1[15]); PIN(rm); SBAR();
;         } else {
;             LDV(7); PVM(4); rm = max3f(pb0[0], pb0[1], pb1[0]); rm2 = max3f(pb0[2], pb0[3], pb1[1]); rm = max3f(rm, pb1[2], pb1[3]); rm2 = max3f(rm2, pb0[4], pb0[5]); PIN(rm); PIN(rm2); SBAR();
;             PVM(5); rm = max3f(rm, pb0[6], pb0[7]); rm2 = max3f(rm2, pb1[4], pb1[5]); rm = max3f(rm, pb1[6], pb1[7]); rm2 = max3f(rm2, pb0[8], pb0[9]); PIN(rm); PIN(rm2); SBAR();
;             PVM(6); rm = max3f(rm, pb0[10], pb0[11]); rm2 = max3f(rm2, pb1[8], pb1[9]); rm = max3f(rm, pb1[10], pb1[11]); rm2 = max3f(rm2, pb0[12], pb0[13]); PIN(rm); PIN(rm2); SBAR();
;             PVM(7); rm = max3f(rm, pb0[14], pb0[15]); rm2 = max3f(rm2, pb1[12], pb1[13]); rm = max3f(rm, pb1[14], pb1[15]); PIN(rm); PIN(rm2); SBAR();
;         }
;     ...
;         rm = swapmax(max3f(rm, rm2, rm2));
;         if (KIND == 2) {
;             const u32x2 kx = *(const LAS u32x2*)(shm3 + sc + 32768);
;             const float xk0 = __uint_as_float(kx.x << 16) + __uint_as_float(kx.x & 0xffff0000u) + __uint_as_float(kx.y << 16);
;             const float ltot = swapsum(lsum);
;             const bool ok = (qkmax + cb + xk0) < (mhat + __builtin_amdgcn_logf(ltot) - 54.0f);
;             const bool allok = __all(ok) && !(ATT_TILE(i) > wt_hi);
.Lct2_357:
	s_add_i32 s19, s20, 2
	s_cmp_lt_i32 s19, 0
	s_cselect_b64 s[38:39], -1, 0
	s_cmp_gt_i32 s19, s36
	s_waitcnt lgkmcnt(4)
	v_mfma_f32_32x32x16_bf16 v[52:67], v[84:87], v[190:193], v[52:67]
	s_cselect_b64 vcc, -1, 0
	s_or_b64 vcc, s[38:39], vcc
	s_cbranch_vccz .Lct2x_nomask
	v_mov_b32_e32 v116, v245
	v_mov_b32_e32 v117, v245
	v_mov_b32_e32 v118, v245
	v_mov_b32_e32 v119, v245
	v_mov_b32_e32 v120, v245
	v_mov_b32_e32 v121, v245
	v_mov_b32_e32 v122, v245
	v_mov_b32_e32 v123, v245
	v_mov_b32_e32 v124, v245
	v_mov_b32_e32 v125, v245
	v_mov_b32_e32 v126, v245
	v_mov_b32_e32 v127, v245
	v_mov_b32_e32 v128, v245
	v_mov_b32_e32 v129, v245
	v_mov_b32_e32 v130, v245
	v_mov_b32_e32 v131, v245
	v_mov_b32_e32 v4, v245
	v_mov_b32_e32 v5, v245
	v_mov_b32_e32 v6, v245
	v_mov_b32_e32 v7, v245
	v_mov_b32_e32 v8, v245
	v_mov_b32_e32 v9, v245
	v_mov_b32_e32 v10, v245
	v_mov_b32_e32 v11, v245
	v_mov_b32_e32 v12, v245
	v_mov_b32_e32 v13, v245
	v_mov_b32_e32 v14, v245
	v_mov_b32_e32 v15, v245
	v_mov_b32_e32 v16, v245
	v_mov_b32_e32 v17, v245
	v_mov_b32_e32 v18, v245
	v_mov_b32_e32 v19, v245
.Lct2x_nomask:
	v_add_f32_e32 v169, v169, v68
	ds_read_b64_tr_b16 v[96:97], v164 offset:23552
	ds_read_b64_tr_b16 v[98:99], v164 offset:24064
	v_max3_f32 v84, v116, v117, v4
	v_max3_f32 v85, v118, v119, v5
	v_max3_f32 v84, v84, v6, v7
	v_max3_f32 v85, v85, v120, v121
	s_waitcnt lgkmcnt(4)
	v_mfma_f32_32x32x16_bf16 v[36:51], v[88:91], v[190:193], v[36:51]
	v_max3_f32 v84, v84, v122, v123
	v_max3_f32 v85, v85, v8, v9
	v_max3_f32 v84, v84, v10, v11
	v_max3_f32 v85, v85, v124, v125
	s_waitcnt lgkmcnt(2)
	v_mfma_f32_32x32x16_bf16 v[52:67], v[92:95], v[152:155], v[52:67]
	v_max3_f32 v84, v84, v126, v127
	v_max3_f32 v85, v85, v12, v13
	v_max3_f32 v84, v84, v14, v15
	v_max3_f32 v85, v85, v128, v129
	s_waitcnt lgkmcnt(0)
	v_mfma_f32_32x32x16_bf16 v[36:51], v[96:99], v[152:155], v[36:51]
	v_max3_f32 v84, v84, v130, v131
	v_max3_f32 v85, v85, v16, v17
	v_max3_f32 v84, v84, v18, v19
	v_mov_b32_e32 v86, s18
	ds_read_b64 v[86:87], v86 offset:32768
	v_max3_f32 v84, v84, v85, v85
	s_mov_b64 s[18:19], exec
	v_mov_b32_e32 v85, v84
	s_nop 1
	v_permlane32_swap_b32_e32 v84, v85
	s_waitcnt lgkmcnt(0)
	v_lshlrev_b32_e32 v88, 16, v86
	v_and_b32_e32 v86, 0xffff0000, v86
	v_add_f32_e32 v164, v88, v86
	v_lshlrev_b32_e32 v86, 16, v87
	v_mov_b32_e32 v87, v169
	v_mov_b32_e32 v88, v169
	s_nop 1
	v_permlane32_swap_b32_e32 v87, v88
	v_add_f32_e32 v87, v87, v88
	v_log_f32_e32 v87, v87
	s_nop 0
	v_pk_add_f32 v[86:87], v[164:165], v[86:87]
	s_nop 0
	v_pk_add_f32 v[86:87], v[202:203], v[86:87]
	s_nop 0
	v_cmp_lt_f32_e32 vcc, v86, v87
	s_and_saveexec_b64 s[38:39], s[46:47]
	s_cbranch_execz .Lct2_359
	s_sub_i32 s26, s25, 24
	s_and_b32 s26, s26, 24
	s_lshl_b32 s26, s26, 2
	s_add_i32 s34, s37, s26
	s_cmp_eq_u64 vcc, s[18:19]
	s_cselect_b64 s[18:19], -1, 0
	s_cmp_ge_i32 s35, s40
	s_cselect_b64 s[26:27], -1, 0
	s_and_b64 s[18:19], s[18:19], s[26:27]
	v_cndmask_b32_e64 v86, 0, 1, s[18:19]
	v_mov_b32_e32 v87, s34
	ds_write_b32 v87, v86
